# v32
# speedup vs baseline: 1.0095x; 1.0075x over previous
.LBB0_171:
	s_or_b64 exec, exec, s[8:9]
	v_add_u32_e32 v136, s30, v44
	v_lshlrev_b32_e32 v44, 7, v38
	v_and_b32_e32 v45, 7, v38
	v_bitop3_b32 v38, v38, v1, 7 bitop3:0x6c
	v_lshl_or_b32 v38, v38, 4, v44
	v_add_u32_e32 v138, 0, v38
	v_xor_b32_e32 v38, v43, v1
	v_bitop3_b32 v1, v43, v1, 4 bitop3:0x36
	v_lshlrev_b32_e32 v144, 4, v38
	v_lshlrev_b32_e32 v146, 4, v1
	v_xor_b32_e32 v1, 16, v214
	v_add_u32_e32 v38, 64, v39
	v_cmp_lt_i32_e64 s[8:9], v1, v38
	s_lshr_b32 s30, s16, 6
	s_add_i32 s80, s30, -2
	v_cndmask_b32_e64 v1, v214, v1, s[8:9]
	v_lshlrev_b32_e32 v135, 2, v1
	v_xor_b32_e32 v1, 32, v214
	v_cmp_lt_i32_e64 s[8:9], v1, v38
	v_and_b32_e32 v46, 4, v42
	v_lshlrev_b32_e32 v42, 1, v42
	v_cndmask_b32_e64 v1, v214, v1, s[8:9]
	s_add_u32 s8, s20, s13
	s_addc_u32 s9, s21, 0
	v_lshl_add_u64 v[106:107], s[8:9], 0, v[36:37]
	s_and_b32 s8, s52, 15
	v_and_b32_e32 v42, 2, v42
	s_lshl_b32 s8, s8, 7
	v_or_b32_e32 v47, v42, v46
	s_add_u32 s8, s20, s8
	v_bitop3_b32 v42, v42, v45, v46 bitop3:0x36
	v_bitop3_b32 v45, v47, v45, 1 bitop3:0x36
	s_addc_u32 s9, s21, 0
	v_and_b32_e32 v40, 8, v40
	v_lshlrev_b32_e32 v42, 4, v42
	v_lshlrev_b32_e32 v45, 4, v45
	s_add_u32 s8, s8, s12
	v_or3_b32 v42, v42, v44, v40
	v_or3_b32 v40, v45, v44, v40
	s_addc_u32 s9, s9, 0
	v_mov_b32_e32 v46, v0
	v_mov_b32_e32 v47, v0
	v_mov_b32_e32 v48, v0
	v_mov_b32_e32 v49, v0
	v_add_u32_e32 v139, 0, v42
	v_add_u32_e32 v140, 0, v40
	v_lshlrev_b32_e32 v137, 2, v43
	v_lshl_add_u32 v142, v43, 4, 0
	v_lshlrev_b32_e32 v143, 7, v41
	v_or_b32_e32 v148, v136, v41
	v_lshlrev_b32_e32 v101, 2, v1
	v_lshl_add_u64 v[108:109], s[8:9], 0, v[34:35]
	v_mov_b32_e32 v1, v0
	v_mov_b64_e32 v[64:65], v[48:49]
	v_mov_b64_e32 v[42:43], v[46:47]
	v_mov_b64_e32 v[60:61], v[48:49]
	v_mov_b64_e32 v[38:39], v[46:47]
	v_mov_b64_e32 v[56:57], v[48:49]
	v_mov_b64_e32 v[34:35], v[46:47]
	v_mov_b64_e32 v[52:53], v[48:49]
	v_or_b32_e32 v141, 31, v136
	v_add_u32_e32 v145, 0, v144
	v_add_u32_e32 v147, 0, v146
	v_or_b32_e32 v149, 16, v148
	v_add_u32_e32 v150, 0, v143
	v_mov_b32_e32 v99, v0
	v_mov_b32_e32 v110, 0xff800000
	s_mov_b32 s65, 3
	s_movk_i32 s81, 0x7f
	s_xor_b64 s[12:13], vcc, -1
	v_mov_b64_e32 v[62:63], v[46:47]
	v_mov_b64_e32 v[44:45], v[48:49]
	v_mov_b64_e32 v[58:59], v[46:47]
	v_mov_b64_e32 v[40:41], v[48:49]
	v_mov_b64_e32 v[54:55], v[46:47]
	v_mov_b64_e32 v[36:37], v[48:49]
	v_mov_b64_e32 v[50:51], v[46:47]
	v_mov_b32_e32 v111, 0xff800000
	v_mov_b64_e32 v[104:105], v[0:1]
	ds_write_b128 v138, v[2:5] offset:8704
	ds_write_b64 v139, v[6:7] offset:25088
	ds_write_b64 v140, v[8:9] offset:25088
	s_waitcnt lgkmcnt(0)
	v_lshl_add_u64 v[108:109], v[108:109], 0, v[98:99]
	v_lshl_add_u64 v[106:107], v[106:107], 0, v[98:99]
	s_mov_b64 s[82:83], 0x1b767000
	v_lshl_add_u64 v[108:109], v[108:109], 0, s[82:83]
	s_mov_b64 s[82:83], 0x27b27000
	v_lshl_add_u64 v[106:107], v[106:107], 0, s[82:83]
	s_mov_b64 s[82:83], 0x20000
	v_lshl_add_u64 v[190:191], v[108:109], 0, s[82:83]
	v_add_u32_e32 v186, v145, v143
	v_add_u32_e32 v187, v147, v143
	v_add_u32_e32 v188, v150, v144
	v_add_u32_e32 v189, v150, v146
	s_waitcnt vmcnt(0)
	s_barrier
	s_branch .LBB0_174

.LBB0_173:
	s_add_i32 s65, s65, 2
	s_addk_i32 s81, 0x80
	v_lshl_add_u64 v[106:107], v[106:107], 0, s[66:67]
	v_add_u32_e32 v142, 0x200, v142
	s_cmp_ge_u32 s82, s30
	v_lshl_add_u64 v[108:109], v[108:109], 0, s[44:45]
	v_lshl_add_u64 v[190:191], v[190:191], 0, s[44:45]
	s_cbranch_scc1 .LBB0_295
.LBB0_174:
	s_add_i32 s82, s65, -1
	s_cmp_ge_u32 s82, s30
	s_cbranch_scc1 .Lattn1_skip1
	global_load_dwordx4 v[2:5], v[108:109], off offset:2048
	global_load_dwordx4 v[6:9], v[106:107], off offset:2304

.LBB0_182:
	s_andn2_b64 vcc, exec, s[8:9]
	s_waitcnt lgkmcnt(0)
	s_barrier
	s_cbranch_vccnz .LBB0_173
	s_cmp_ge_u32 s65, s30
	s_cbranch_scc1 .Lattn1_skip2
	global_load_dwordx4 v[10:13], v[190:191], off offset:2048
	global_load_dwordx4 v[14:17], v[106:107], off offset:2432

.LBB0_203:
	s_or_b64 exec, exec, s[8:9]
	v_lshlrev_b32_e32 v45, 7, v36
	v_and_b32_e32 v46, 7, v36
	v_bitop3_b32 v36, v36, v1, 7 bitop3:0x6c
	v_lshl_or_b32 v36, v36, 4, v45
	v_add_u32_e32 v138, 0, v36
	v_xor_b32_e32 v36, v43, v1
	v_bitop3_b32 v1, v43, v1, 4 bitop3:0x36
	v_lshlrev_b32_e32 v144, 4, v36
	v_lshlrev_b32_e32 v146, 4, v1
	v_xor_b32_e32 v1, 16, v214
	v_add_u32_e32 v36, 64, v37
	v_cmp_lt_i32_e64 s[8:9], v1, v36
	v_and_b32_e32 v47, 4, v42
	v_lshlrev_b32_e32 v42, 1, v42
	v_cndmask_b32_e64 v1, v214, v1, s[8:9]
	v_lshlrev_b32_e32 v135, 2, v1
	v_xor_b32_e32 v1, 32, v214
	v_cmp_lt_i32_e64 s[8:9], v1, v36
	v_and_b32_e32 v42, 2, v42
	v_or_b32_e32 v48, v42, v47
	v_cndmask_b32_e64 v1, v214, v1, s[8:9]
	s_add_u32 s8, s20, s17
	s_addc_u32 s9, s21, s16
	v_lshl_add_u64 v[106:107], s[8:9], 0, v[40:41]
	s_and_b32 s8, s52, 15
	s_lshl_b32 s8, s8, 7
	s_add_u32 s8, s20, s8
	v_bitop3_b32 v42, v42, v46, v47 bitop3:0x36
	v_bitop3_b32 v46, v48, v46, 1 bitop3:0x36
	s_addc_u32 s9, s21, 0
	v_and_b32_e32 v38, 8, v38
	v_lshlrev_b32_e32 v42, 4, v42
	v_lshlrev_b32_e32 v46, 4, v46
	s_add_u32 s8, s8, s12
	v_add_u32_e32 v136, 0x400, v44
	v_or3_b32 v42, v42, v45, v38
	v_or3_b32 v38, v46, v45, v38
	s_addc_u32 s9, s9, s13
	v_mov_b32_e32 v46, v0
	v_mov_b32_e32 v47, v0
	v_mov_b32_e32 v48, v0
	v_mov_b32_e32 v49, v0
	v_add_u32_e32 v139, 0, v42
	v_add_u32_e32 v140, 0, v38
	v_add_u32_e32 v141, 0x41f, v44
	v_lshlrev_b32_e32 v137, 2, v43
	v_lshl_add_u32 v142, v43, 4, 0
	v_lshlrev_b32_e32 v143, 7, v39
	v_or_b32_e32 v148, v136, v39
	v_lshlrev_b32_e32 v101, 2, v1
	v_add_u32_e32 v151, 0x3c1, v44
	v_lshl_add_u64 v[108:109], s[8:9], 0, v[34:35]
	v_mov_b32_e32 v1, v0
	v_mov_b64_e32 v[64:65], v[48:49]
	v_mov_b64_e32 v[42:43], v[46:47]
	v_mov_b64_e32 v[60:61], v[48:49]
	v_mov_b64_e32 v[38:39], v[46:47]
	v_mov_b64_e32 v[56:57], v[48:49]
	v_mov_b64_e32 v[34:35], v[46:47]
	v_mov_b64_e32 v[52:53], v[48:49]
	v_add_u32_e32 v145, 0, v144
	v_add_u32_e32 v147, 0, v146
	v_or_b32_e32 v149, 16, v148
	v_add_u32_e32 v150, 0, v143
	v_mov_b32_e32 v99, v0
	v_mov_b32_e32 v110, 0xff800000
	s_mov_b32 s30, 0
	s_movk_i32 s65, 0x7f
	s_xor_b64 s[12:13], vcc, -1
	v_mov_b64_e32 v[62:63], v[46:47]
	v_mov_b64_e32 v[44:45], v[48:49]
	v_mov_b64_e32 v[58:59], v[46:47]
	v_mov_b64_e32 v[40:41], v[48:49]
	v_mov_b64_e32 v[54:55], v[46:47]
	v_mov_b64_e32 v[36:37], v[48:49]
	v_mov_b64_e32 v[50:51], v[46:47]
	v_mov_b32_e32 v111, 0xff800000
	v_mov_b64_e32 v[104:105], v[0:1]
	ds_write_b128 v138, v[2:5] offset:8704
	ds_write_b64 v139, v[6:7] offset:25088
	ds_write_b64 v140, v[8:9] offset:25088
	s_waitcnt lgkmcnt(0)
	v_lshl_add_u64 v[108:109], v[108:109], 0, v[98:99]
	v_lshl_add_u64 v[106:107], v[106:107], 0, v[98:99]
	s_mov_b64 s[82:83], 0x1b767000
	v_lshl_add_u64 v[108:109], v[108:109], 0, s[82:83]
	s_mov_b64 s[82:83], 0x2fb27000
	v_lshl_add_u64 v[106:107], v[106:107], 0, s[82:83]
	s_mov_b64 s[82:83], 0x20000
	v_lshl_add_u64 v[190:191], v[108:109], 0, s[82:83]
	v_add_u32_e32 v186, v145, v143
	v_add_u32_e32 v187, v147, v143
	v_add_u32_e32 v188, v150, v144
	v_add_u32_e32 v189, v150, v146
	s_waitcnt vmcnt(0)
	s_barrier
	s_branch .LBB0_206

.LBB0_205:
	s_add_i32 s30, s30, 2
	v_lshl_add_u64 v[106:107], v[106:107], 0, s[66:67]
	v_add_u32_e32 v142, 0x200, v142
	s_addk_i32 s65, 0x80
	v_lshl_add_u64 v[108:109], v[108:109], 0, s[44:45]
	v_lshl_add_u64 v[190:191], v[190:191], 0, s[44:45]
	s_and_b64 vcc, exec, s[16:17]
	s_cbranch_vccnz .LBB0_223
.LBB0_206:
	s_cmp_lt_u32 s30, 15
	s_cselect_b64 s[78:79], -1, 0
	s_cmp_gt_u32 s30, 14
	s_cselect_b64 s[16:17], -1, 0
	s_and_b64 vcc, exec, s[16:17]
	s_cbranch_vccnz .Lattn2_skip1
	global_load_dwordx4 v[2:5], v[108:109], off offset:2048
	global_load_dwordx4 v[6:9], v[106:107], off offset:2304

.LBB0_214:
	s_andn2_b64 vcc, exec, s[8:9]
	s_waitcnt lgkmcnt(0)
	s_barrier
	s_cbranch_vccnz .LBB0_205
	s_cmp_gt_u32 s30, 13
	s_cbranch_scc1 .Lattn2_skip2
	global_load_dwordx4 v[10:13], v[190:191], off offset:2048
	global_load_dwordx4 v[14:17], v[106:107], off offset:2432
